# mlstm_out: mlstm_gates loads issued before the prefetch batch (vmcnt(63) instead of draining the batch)
# baseline (speedup 1.0000x reference)
.LBB0_1153:
	s_mov_b64 s[10:11], s[62:63]
	s_load_dwordx2 s[24:25], s[10:11], 0xc0
	s_load_dwordx2 s[30:31], s[10:11], 0x38
	s_load_dwordx2 s[34:35], s[10:11], 0x28
	s_load_dwordx2 s[42:43], s[10:11], 0x30
	v_mov_b32_e32 v64, v208
	s_and_b32 s13, s27, 0xfffff800
	s_and_b32 s6, s26, 0x780
	s_lshr_b32 s7, s28, 4
	v_ashrrev_i32_e32 v159, 6, v64
	s_bfe_u32 s12, s28, 0x20004
	s_or_b32 s5, s13, s6
	v_lshlrev_b32_e32 v95, 4, v159
	s_lshl_b32 s29, s12, 7
	s_bfe_u32 s96, s7, 0x10001
	v_and_b32_e32 v50, 63, v64
	v_add_u32_e32 v72, s5, v95
	s_or_b32 s7, s96, 6
	v_mov_b32_e32 v6, s29
	v_lshlrev_b32_e32 v160, 1, v50
	s_movk_i32 s0, 0xfe
	v_ashrrev_i32_e32 v73, 31, v72
	s_or_b32 s10, s96, 8
	v_mov_b32_e32 v166, s7
	v_bitop3_b32 v8, v160, s0, v6 bitop3:0xc8
	v_lshlrev_b32_e32 v6, 8, v72
	v_alignbit_b32 v52, v73, v72, 8
	v_mov_b32_e32 v5, v167
	v_mov_b32_e32 v4, s10
	v_and_b32_e32 v9, 0xf000, v6
	v_mad_u64_u32 v[6:7], s[10:11], v52, 49, v[166:167]
	v_mad_u64_u32 v[4:5], s[10:11], v52, 49, v[4:5]
	v_mad_u32_u24 v7, v73, 49, v7
	s_mov_b64 s[2:3], 0x74c2800
	v_mad_u32_u24 v5, v73, 49, v5
	v_lshlrev_b64 v[6:7], 17, v[6:7]
	v_lshlrev_b32_e32 v166, 1, v8
	v_lshlrev_b64 v[4:5], 17, v[4:5]
	v_mov_b32_e32 v19, v167
	v_lshlrev_b32_e32 v18, 1, v9
	v_lshlrev_b32_e32 v51, 3, v64
	v_or_b32_e32 v48, s29, v160
	s_lshl_b64 s[10:11], s[18:19], 2
	v_mov_b64_e32 v[30:31], s[96:97]
	s_waitcnt lgkmcnt(0)
	v_mov_b32_e32 v74, s24
	v_mov_b32_e32 v75, s25
	v_mov_b32_e32 v76, s30
	v_mov_b32_e32 v77, s31
	v_mov_b32_e32 v0, s34
	v_mov_b32_e32 v1, s35
	v_mov_b32_e32 v2, s42
	v_mov_b32_e32 v3, s43
	v_lshl_add_u64 v[20:21], v[74:75], 0, s[2:3]
	v_cmp_gt_i32_e32 vcc, 0x80, v208
	s_and_saveexec_b64 s[30:31], vcc
	v_add_u32_e32 v224, s5, v208
	v_ashrrev_i32_e32 v225, 31, v224
	v_lshlrev_b64 v[224:225], 5, v[224:225]
	v_lshl_add_u64 v[224:225], v[74:75], 0, v[224:225]
	s_lshl_b32 s24, s12, 2
	s_mov_b32 s25, 0
	v_lshl_add_u64 v[224:225], v[224:225], 0, s[24:25]
	s_mov_b64 s[34:35], 0x7300000
	s_or_b32 s24, s12, s36
	v_lshl_add_u64 v[226:227], v[224:225], 0, s[34:35]
	s_lshl_b64 s[24:25], s[24:25], 2
	v_lshl_add_u64 v[228:229], v[2:3], 0, s[24:25]
	global_load_dword v232, v[226:227], off offset:16
	s_nop 0
	global_load_dword v233, v[228:229], off offset:16
	v_add_co_u32_e32 v224, vcc, 0x7300000, v224
	s_nop 1
	v_addc_co_u32_e32 v225, vcc, 0, v225, vcc
	global_load_dword v234, v[224:225], off
	s_nop 0
	global_load_dword v235, v[228:229], off
	s_mov_b64 exec, s[30:31]
	v_lshl_add_u64 v[6:7], v[20:21], 0, v[6:7]
	v_lshl_add_u64 v[4:5], v[20:21], 0, v[4:5]
	v_lshl_add_u64 v[6:7], v[6:7], 0, v[166:167]
	v_lshl_add_u64 v[4:5], v[4:5], 0, v[166:167]
	v_lshl_add_u64 v[6:7], v[6:7], 0, v[18:19]
	v_lshl_add_u64 v[4:5], v[4:5], 0, v[18:19]
	global_load_dword v158, v[6:7], off
	global_load_dword v156, v[6:7], off offset:512
	global_load_dword v154, v[6:7], off offset:1024
	global_load_dword v151, v[6:7], off offset:1536
	global_load_dword v149, v[6:7], off offset:2048
	global_load_dword v147, v[6:7], off offset:2560
	global_load_dword v145, v[6:7], off offset:3072
	global_load_dword v143, v[6:7], off offset:3584
	global_load_dword v157, v[4:5], off
	global_load_dword v155, v[4:5], off offset:512
	global_load_dword v153, v[4:5], off offset:1024
	global_load_dword v152, v[4:5], off offset:1536
	global_load_dword v150, v[4:5], off offset:2048
	global_load_dword v148, v[4:5], off offset:2560
	global_load_dword v146, v[4:5], off offset:3072
	global_load_dword v144, v[4:5], off offset:3584
	v_add_co_u32_e32 v6, vcc, s91, v6
	s_mov_b64 s[2:3], 0x800
	s_nop 0
	v_addc_co_u32_e32 v7, vcc, 0, v7, vcc
	v_add_co_u32_e32 v4, vcc, s91, v4
	v_add_u32_e32 v19, s6, v95
	s_nop 0
	v_addc_co_u32_e32 v5, vcc, 0, v5, vcc
	global_load_dword v141, v[6:7], off
	global_load_dword v139, v[6:7], off offset:512
	global_load_dword v137, v[6:7], off offset:1024
	global_load_dword v135, v[6:7], off offset:1536
	global_load_dword v133, v[6:7], off offset:2048
	global_load_dword v131, v[6:7], off offset:2560
	global_load_dword v129, v[6:7], off offset:3072
	global_load_dword v128, v[6:7], off offset:3584
	global_load_dword v142, v[4:5], off
	global_load_dword v140, v[4:5], off offset:512
	global_load_dword v138, v[4:5], off offset:1024
	global_load_dword v136, v[4:5], off offset:1536
	global_load_dword v134, v[4:5], off offset:2048
	global_load_dword v132, v[4:5], off offset:2560
	global_load_dword v130, v[4:5], off offset:3072
	global_load_dword v79, v[4:5], off offset:3584
	v_and_b32_e32 v4, 0xffffff80, v51
	v_ashrrev_i32_e32 v5, 31, v4
	v_lshlrev_b32_e32 v6, 4, v64
	v_add_u32_e32 v8, 0x1000, v4
	v_and_b32_e32 v10, 0xf0, v6
	v_lshlrev_b64 v[6:7], 1, v[4:5]
	v_ashrrev_i32_e32 v9, 31, v8
	v_or_b32_e32 v6, v6, v10
	v_lshlrev_b64 v[8:9], 1, v[8:9]
	v_lshl_add_u64 v[6:7], v[74:75], 0, v[6:7]
	v_or_b32_e32 v8, v8, v10
	v_lshl_add_u64 v[6:7], v[6:7], 0, s[14:15]
	v_lshl_add_u64 v[8:9], v[74:75], 0, v[8:9]
	v_lshl_add_u64 v[8:9], v[8:9], 0, s[14:15]
	global_load_dwordx4 v[36:39], v[6:7], off
	global_load_dwordx4 v[32:35], v[8:9], off
	v_add_u32_e32 v6, 0x2000, v4
	v_add_u32_e32 v4, 0x3000, v4
	v_ashrrev_i32_e32 v7, 31, v6
	v_ashrrev_i32_e32 v5, 31, v4
	v_lshlrev_b64 v[6:7], 1, v[6:7]
	v_lshlrev_b64 v[4:5], 1, v[4:5]
	v_or_b32_e32 v6, v6, v10
	v_or_b32_e32 v4, v4, v10
	v_lshl_add_u64 v[6:7], v[74:75], 0, v[6:7]
	v_lshl_add_u64 v[4:5], v[74:75], 0, v[4:5]
	v_lshl_add_u64 v[6:7], v[6:7], 0, s[14:15]
	v_lshl_add_u64 v[4:5], v[4:5], 0, s[14:15]
	global_load_dwordx4 v[44:47], v[6:7], off
	global_load_dwordx4 v[40:43], v[4:5], off
	v_lshlrev_b32_e32 v4, 2, v48
	v_mov_b32_e32 v5, v167
	s_waitcnt vmcnt(40)
	v_lshl_add_u64 v[0:1], v[0:1], 0, v[4:5]
	v_lshl_add_u64 v[4:5], v[0:1], 0, s[2:3]
	v_lshl_add_u64 v[8:9], v[0:1], 0, s[10:11]
	v_lshl_add_u64 v[14:15], v[4:5], 0, s[10:11]
	s_lshl_b64 s[10:11], s[20:21], 2
	v_lshl_add_u64 v[16:17], v[0:1], 0, s[10:11]
	v_lshl_add_u64 v[22:23], v[4:5], 0, s[10:11]
	s_lshl_b64 s[10:11], s[22:23], 2
	v_lshl_add_u64 v[6:7], s[16:17], 2, v[0:1]
	v_lshl_add_u64 v[4:5], v[4:5], 0, s[10:11]
	v_lshl_add_u64 v[24:25], v[0:1], 0, s[10:11]
	global_load_dwordx2 v[10:11], v[6:7], off
	global_load_dwordx2 v[12:13], v[8:9], off
	global_load_dwordx2 v[0:1], v[14:15], off
	s_nop 0
	global_load_dwordx2 v[6:7], v[6:7], off offset:2048
	s_nop 0
	global_load_dwordx2 v[16:17], v[16:17], off
	s_nop 0
	global_load_dwordx2 v[14:15], v[24:25], off
	s_nop 0
	global_load_dwordx2 v[4:5], v[4:5], off
	s_nop 0
	global_load_dwordx2 v[8:9], v[22:23], off
	v_cmp_gt_i32_e64 s[10:11], 3, v19
	s_and_saveexec_b64 s[6:7], s[10:11]
	s_xor_b64 s[6:7], exec, s[6:7]
	v_mov_b64_e32 v[30:31], s[96:97]
	s_or_saveexec_b64 s[6:7], s[6:7]
	v_add_u32_e32 v22, s13, v19
	v_ashrrev_i32_e32 v23, 31, v22
	v_lshl_add_u64 v[28:29], v[22:23], 0, -3
	v_lshl_add_u64 v[26:27], v[22:23], 0, -2
	v_lshl_add_u64 v[24:25], v[22:23], 0, -1
	v_mov_b32_e32 v100, 0
	v_alignbit_b32 v55, v29, v28, 8
	v_lshlrev_b32_e32 v54, 9, v28
	v_alignbit_b32 v53, v27, v26, 8
	v_lshlrev_b32_e32 v28, 9, v26
	v_alignbit_b32 v26, v25, v24, 8
	v_lshlrev_b32_e32 v19, 9, v24
	v_mov_b32_e32 v102, 0
	v_mov_b32_e32 v103, 0
	s_xor_b64 exec, exec, s[6:7]
	s_cbranch_execz .LBB0_1157
	v_mad_u64_u32 v[56:57], s[24:25], v55, 49, s[96:97]
	v_mad_u32_u24 v57, v29, 49, v57
	v_lshlrev_b64 v[56:57], 17, v[56:57]
	v_lshl_add_u64 v[56:57], v[20:21], 0, v[56:57]
	v_and_b32_e32 v58, 0x1fe00, v54
	v_mov_b32_e32 v59, v167
	v_lshl_add_u64 v[56:57], v[56:57], 0, v[58:59]
	v_lshl_add_u64 v[56:57], v[56:57], 0, v[166:167]
	global_load_dword v100, v[56:57], off
	v_mad_u64_u32 v[56:57], s[24:25], v53, 49, s[96:97]
	v_mad_u32_u24 v57, v27, 49, v57
	v_lshlrev_b64 v[56:57], 17, v[56:57]
	v_lshl_add_u64 v[56:57], v[20:21], 0, v[56:57]
	v_and_b32_e32 v58, 0x1fe00, v28
	v_lshl_add_u64 v[56:57], v[56:57], 0, v[58:59]
	v_lshl_add_u64 v[56:57], v[56:57], 0, v[166:167]
	global_load_dword v102, v[56:57], off
	v_mad_u64_u32 v[56:57], s[24:25], v26, 49, s[96:97]
	v_mad_u32_u24 v57, v25, 49, v57
	v_lshlrev_b64 v[56:57], 17, v[56:57]
	v_lshl_add_u64 v[56:57], v[20:21], 0, v[56:57]
	v_and_b32_e32 v58, 0x1fe00, v19
	v_lshl_add_u64 v[56:57], v[56:57], 0, v[58:59]
	v_lshl_add_u64 v[56:57], v[56:57], 0, v[166:167]
	global_load_dword v103, v[56:57], off

.LBB0_1161:
	s_or_b64 exec, exec, s[6:7]
	v_mad_u64_u32 v[26:27], s[6:7], v56, 49, 0
	v_mad_u32_u24 v27, v23, 49, v27
	v_lshl_add_u64 v[22:23], v[48:49], 0, v[26:27]
	v_lshlrev_b64 v[22:23], 17, v[22:23]
	v_lshl_add_u64 v[22:23], v[20:21], 0, v[22:23]
	v_mov_b32_e32 v31, v167
	v_lshl_add_u64 v[22:23], v[22:23], 0, v[30:31]
	v_lshl_add_u64 v[22:23], v[22:23], 0, v[166:167]
	v_mad_u64_u32 v[24:25], s[6:7], v52, 49, 0
	global_load_dword v86, v[22:23], off
	global_load_dword v70, v[22:23], off offset:512
	global_load_dword v68, v[22:23], off offset:1024
	global_load_dword v67, v[22:23], off offset:1536
	global_load_dword v66, v[22:23], off offset:2048
	global_load_dword v65, v[22:23], off offset:2560
	global_load_dword v63, v[22:23], off offset:3072
	global_load_dword v62, v[22:23], off offset:3584
	v_add_co_u32_e32 v22, vcc, s91, v22
	v_mad_u32_u24 v25, v73, 49, v25
	s_nop 0
	v_addc_co_u32_e32 v23, vcc, 0, v23, vcc
	s_or_b32 s96, s96, 4
	global_load_dword v61, v[22:23], off
	global_load_dword v60, v[22:23], off offset:512
	global_load_dword v59, v[22:23], off offset:1024
	global_load_dword v58, v[22:23], off offset:1536
	global_load_dword v57, v[22:23], off offset:2048
	global_load_dword v56, v[22:23], off offset:2560
	global_load_dword v55, v[22:23], off offset:3072
	global_load_dword v54, v[22:23], off offset:3584
	v_lshl_add_u64 v[22:23], v[24:25], 0, s[96:97]
	v_lshlrev_b64 v[22:23], 17, v[22:23]
	v_lshl_add_u64 v[20:21], v[20:21], 0, v[22:23]
	v_mov_b32_e32 v19, v167
	v_lshl_add_u64 v[18:19], v[20:21], 0, v[18:19]
	v_lshl_add_u64 v[18:19], v[18:19], 0, v[166:167]
	global_load_dword v24, v[18:19], off
	global_load_dword v20, v[18:19], off offset:512
	global_load_dword v21, v[18:19], off offset:1024
	global_load_dword v22, v[18:19], off offset:1536
	global_load_dword v25, v[18:19], off offset:2048
	global_load_dword v23, v[18:19], off offset:2560
	global_load_dword v26, v[18:19], off offset:3072
	global_load_dword v27, v[18:19], off offset:3584
	v_add_co_u32_e32 v18, vcc, 0x1000, v18
	s_nop 1
	v_addc_co_u32_e32 v19, vcc, 0, v19, vcc
	global_load_dword v29, v[18:19], off
	global_load_dword v28, v[18:19], off offset:512
	global_load_dword v30, v[18:19], off offset:1024
	global_load_dword v31, v[18:19], off offset:1536
	global_load_dword v49, v[18:19], off offset:2048
	global_load_dword v48, v[18:19], off offset:2560
	global_load_dword v52, v[18:19], off offset:3072
	global_load_dword v53, v[18:19], off offset:3584
	v_mov_b32_e32 v19, v208
	s_nop 0
	v_cmp_gt_i32_e64 s[10:11], s83, v19
	v_lshl_add_u32 v18, v19, 2, 0
	s_and_saveexec_b64 s[6:7], s[10:11]
	s_cbranch_execz .LBB0_1165
	s_mov_b32 s0, 0xbfb8aa3b
	v_and_b32_e32 v109, 64, v214
	v_add_u32_e32 v111, -1, v214
	v_cmp_lt_i32_e32 vcc, v111, v109
	v_and_b32_e32 v110, 63, v19
	v_cmp_eq_u32_e64 s[12:13], 63, v19
	s_waitcnt vmcnt(63)
	v_add_f32_e32 v2, v232, v233
	v_mul_f32_e64 v3, |v2|, s0
	v_exp_f32_e32 v105, v3
	v_cndmask_b32_e32 v3, v111, v214, vcc
	v_lshlrev_b32_e32 v108, 2, v3
	v_min_f32_e32 v111, 0, v2
	v_add_f32_e32 v112, 1.0, v105
	v_add_f32_e32 v113, -1.0, v112
	v_frexp_mant_f32_e32 v114, v112
	v_cvt_f64_f32_e32 v[2:3], v112
	s_mov_b32 s0, 0x3f2aaaab
	v_sub_f32_e32 v115, v113, v112
	v_frexp_exp_i32_f64_e32 v2, v[2:3]
	v_cmp_gt_f32_e32 vcc, s0, v114
	v_sub_f32_e32 v113, v105, v113
	v_add_f32_e32 v3, 1.0, v115
	v_subbrev_co_u32_e32 v2, vcc, 0, v2, vcc
	v_add_f32_e32 v3, v113, v3
	v_sub_u32_e32 v113, 0, v2
	v_cvt_f32_i32_e32 v2, v2
	v_ldexp_f32 v112, v112, v113
	v_ldexp_f32 v3, v3, v113
	v_add_f32_e32 v113, -1.0, v112
	v_add_f32_e32 v114, 1.0, v112
	v_add_f32_e32 v115, 1.0, v113
	v_add_f32_e32 v116, -1.0, v114
	v_sub_f32_e32 v115, v112, v115
	v_sub_f32_e32 v112, v112, v116
	v_mul_f32_e32 v116, 0x3f317218, v2
	v_add_f32_e32 v115, v3, v115
	v_add_f32_e32 v3, v3, v112
	v_fma_f32 v112, v2, s56, -v116
	v_add_f32_e32 v117, v113, v115
	v_add_f32_e32 v118, v114, v3
	v_fmac_f32_e32 v112, 0xb102e308, v2
	v_sub_f32_e32 v2, v117, v113
	v_sub_f32_e32 v113, v118, v114
	v_rcp_f32_e32 v114, v118
	v_add_f32_e32 v119, v116, v112
	v_sub_f32_e32 v3, v3, v113
	v_sub_f32_e32 v113, v119, v116
	v_sub_f32_e32 v112, v112, v113
	v_mul_f32_e32 v113, v117, v114
	v_sub_f32_e32 v2, v115, v2
	v_mul_f32_e32 v115, v118, v113
	v_fma_f32 v116, v113, v118, -v115
	v_fmac_f32_e32 v116, v113, v3
	v_add_f32_e32 v120, v115, v116
	v_sub_f32_e32 v121, v117, v120
	v_sub_f32_e32 v115, v120, v115
	v_sub_f32_e32 v117, v117, v121
	v_sub_f32_e32 v115, v115, v116
	v_sub_f32_e32 v116, v117, v120
	v_add_f32_e32 v2, v2, v116
	v_add_f32_e32 v2, v115, v2
	v_add_f32_e32 v115, v121, v2
	v_mul_f32_e32 v116, v114, v115
	v_sub_f32_e32 v117, v121, v115
	v_mul_f32_e32 v120, v118, v116
	v_add_f32_e32 v2, v2, v117
	v_add_f32_e32 v117, v113, v116
	v_fma_f32 v118, v116, v118, -v120
	v_sub_f32_e32 v113, v117, v113
	v_fmac_f32_e32 v118, v116, v3
	v_sub_f32_e32 v3, v116, v113
	v_add_f32_e32 v113, v120, v118
	v_sub_f32_e32 v116, v113, v120
	v_sub_f32_e32 v120, v115, v113
	v_sub_f32_e32 v115, v115, v120
	v_sub_f32_e32 v113, v115, v113
	v_sub_f32_e32 v116, v116, v118
	v_add_f32_e32 v2, v2, v113
	v_add_f32_e32 v2, v116, v2
	v_add_f32_e32 v2, v120, v2
	v_mul_f32_e32 v2, v114, v2
	v_add_f32_e32 v2, v3, v2
	v_add_f32_e32 v3, v117, v2
	v_mul_f32_e32 v113, v3, v3
	v_fmamk_f32 v116, v113, 0x3e9b6dac, v217
	v_sub_f32_e32 v114, v3, v117
	v_ldexp_f32 v115, v3, 1
	v_mul_f32_e32 v3, v3, v113
	v_fmaak_f32 v113, v113, v116, 0x3f2aaada
	v_mul_f32_e32 v3, v3, v113
	v_add_f32_e32 v113, v115, v3
	v_sub_f32_e32 v2, v2, v114
	v_sub_f32_e32 v114, v113, v115
	v_ldexp_f32 v2, v2, 1
	v_sub_f32_e32 v3, v3, v114
	v_add_f32_e32 v2, v2, v3
	v_add_f32_e32 v3, v113, v2
	v_sub_f32_e32 v113, v3, v113
	v_add_f32_e32 v114, v119, v3
	v_sub_f32_e32 v2, v2, v113
	v_sub_f32_e32 v113, v114, v119
	v_sub_f32_e32 v115, v114, v113
	v_sub_f32_e32 v3, v3, v113
	v_add_f32_e32 v113, v112, v2
	v_sub_f32_e32 v115, v119, v115
	v_sub_f32_e32 v116, v113, v112
	v_add_f32_e32 v3, v3, v115
	v_sub_f32_e32 v115, v113, v116
	v_sub_f32_e32 v2, v2, v116
	v_sub_f32_e32 v112, v112, v115
	v_add_f32_e32 v3, v113, v3
	v_add_f32_e32 v2, v2, v112
	v_add_f32_e32 v112, v114, v3
	v_sub_f32_e32 v113, v112, v114
	v_sub_f32_e32 v3, v3, v113
	v_add_f32_e32 v2, v2, v3
	v_add_f32_e32 v2, v112, v2
	v_cmp_neq_f32_e32 vcc, s55, v105
	s_nop 1
	v_cndmask_b32_e32 v2, v209, v2, vcc
	v_cmp_ngt_f32_e32 vcc, -1.0, v105
	s_nop 1
	v_cndmask_b32_e32 v2, v252, v2, vcc
	v_cmp_neq_f32_e32 vcc, -1.0, v105
	s_nop 1
	v_cndmask_b32_e32 v2, v215, v2, vcc
	v_cmp_lt_f32_e64 vcc, |v105|, s57
	s_nop 1
	v_cndmask_b32_e32 v2, v2, v105, vcc
	v_sub_f32_e32 v2, v111, v2
	ds_bpermute_b32 v3, v108, v2
	v_add_u32_e32 v105, -2, v214
	v_cmp_lt_i32_e32 vcc, v105, v109
	s_waitcnt lgkmcnt(0)
	v_add_f32_e32 v3, v2, v3
	v_cndmask_b32_e32 v105, v105, v214, vcc
	v_cmp_eq_u32_e32 vcc, 0, v110
	v_lshlrev_b32_e32 v105, 2, v105
	s_nop 0
	v_cndmask_b32_e32 v2, v3, v2, vcc
	ds_bpermute_b32 v3, v105, v2
	v_add_u32_e32 v105, -4, v214
	v_cmp_lt_i32_e32 vcc, v105, v109
	s_waitcnt lgkmcnt(0)
	v_add_f32_e32 v3, v2, v3
	v_cndmask_b32_e32 v105, v105, v214, vcc
	v_cmp_gt_u32_e32 vcc, 2, v110
	v_lshlrev_b32_e32 v105, 2, v105
	s_nop 0
	v_cndmask_b32_e32 v2, v3, v2, vcc
	ds_bpermute_b32 v3, v105, v2
	v_add_u32_e32 v105, -8, v214
	v_cmp_lt_i32_e32 vcc, v105, v109
	s_waitcnt lgkmcnt(0)
	v_add_f32_e32 v3, v2, v3
	v_cndmask_b32_e32 v105, v105, v214, vcc
	v_cmp_gt_u32_e32 vcc, 4, v110
	v_lshlrev_b32_e32 v105, 2, v105
	s_nop 0
	v_cndmask_b32_e32 v2, v3, v2, vcc
	ds_bpermute_b32 v3, v105, v2
	v_add_u32_e32 v105, -16, v214
	v_cmp_lt_i32_e32 vcc, v105, v109
	s_waitcnt lgkmcnt(0)
	v_add_f32_e32 v3, v2, v3
	v_cndmask_b32_e32 v105, v105, v214, vcc
	v_cmp_gt_u32_e32 vcc, 8, v110
	v_lshlrev_b32_e32 v105, 2, v105
	s_nop 0
	v_cndmask_b32_e32 v2, v3, v2, vcc
	ds_bpermute_b32 v3, v105, v2
	v_subrev_u32_e32 v105, 32, v214
	v_cmp_lt_i32_e32 vcc, v105, v109
	s_waitcnt lgkmcnt(0)
	v_add_f32_e32 v3, v2, v3
	v_cndmask_b32_e32 v105, v105, v214, vcc
	v_cmp_gt_u32_e32 vcc, 16, v110
	v_lshlrev_b32_e32 v105, 2, v105
	s_nop 0
	v_cndmask_b32_e32 v2, v3, v2, vcc
	ds_bpermute_b32 v3, v105, v2
	v_cmp_gt_u32_e32 vcc, 32, v110
	s_waitcnt vmcnt(63)
	v_add_f32_e32 v105, v234, v235
	ds_write_b32 v18, v105 offset:512
	s_waitcnt lgkmcnt(1)
	v_add_f32_e32 v3, v2, v3
	s_and_saveexec_b64 s[24:25], s[12:13]
	ds_write_b32 v167, v3 offset:1024
	s_or_b64 exec, exec, s[24:25]
	v_cndmask_b32_e32 v105, v3, v2, vcc

.LBB0_1307:
	s_mov_b64 s[8:9], s[62:63]
	s_load_dwordx2 s[14:15], s[8:9], 0xc0
	s_load_dwordx2 s[28:29], s[8:9], 0x38
	s_load_dwordx2 s[30:31], s[8:9], 0x28
	s_load_dwordx2 s[34:35], s[8:9], 0x30
	v_mov_b32_e32 v64, v208
	s_and_b32 s11, s25, 0xfffff800
	s_and_b32 s6, s24, 0x780
	s_lshr_b32 s7, s26, 4
	v_ashrrev_i32_e32 v202, 6, v64
	s_bfe_u32 s10, s26, 0x20004
	s_or_b32 s5, s11, s6
	v_lshlrev_b32_e32 v97, 4, v202
	s_lshl_b32 s27, s10, 7
	s_bfe_u32 s96, s7, 0x10001
	v_and_b32_e32 v50, 63, v64
	v_add_u32_e32 v74, s5, v97
	s_or_b32 s7, s96, 6
	v_mov_b32_e32 v6, s27
	v_lshlrev_b32_e32 v203, 1, v50
	s_movk_i32 s0, 0xfe
	v_ashrrev_i32_e32 v75, 31, v74
	s_or_b32 s8, s96, 8
	v_mov_b32_e32 v166, s7
	v_bitop3_b32 v8, v203, s0, v6 bitop3:0xc8
	v_lshlrev_b32_e32 v6, 8, v74
	v_alignbit_b32 v52, v75, v74, 8
	v_mov_b32_e32 v5, v167
	v_mov_b32_e32 v4, s8
	v_and_b32_e32 v9, 0xf000, v6
	v_mad_u64_u32 v[6:7], s[8:9], v52, 49, v[166:167]
	v_mad_u64_u32 v[4:5], s[8:9], v52, 49, v[4:5]
	v_mad_u32_u24 v7, v75, 49, v7
	s_mov_b64 s[2:3], 0x74c2800
	v_mad_u32_u24 v5, v75, 49, v5
	v_lshlrev_b64 v[6:7], 17, v[6:7]
	v_lshlrev_b32_e32 v166, 1, v8
	v_lshlrev_b64 v[4:5], 17, v[4:5]
	v_mov_b32_e32 v19, v167
	v_lshlrev_b32_e32 v18, 1, v9
	v_lshlrev_b32_e32 v51, 3, v64
	v_or_b32_e32 v204, s27, v203
	s_lshl_b64 s[8:9], s[18:19], 2
	v_mov_b64_e32 v[30:31], s[96:97]
	s_waitcnt lgkmcnt(0)
	v_mov_b32_e32 v76, s14
	v_mov_b32_e32 v77, s15
	v_mov_b32_e32 v78, s28
	v_mov_b32_e32 v79, s29
	v_mov_b32_e32 v0, s30
	v_mov_b32_e32 v1, s31
	v_mov_b32_e32 v2, s34
	v_mov_b32_e32 v3, s35
	v_lshl_add_u64 v[20:21], v[76:77], 0, s[2:3]
	v_cmp_gt_i32_e32 vcc, 0x80, v208
	s_and_saveexec_b64 s[28:29], vcc
	v_add_u32_e32 v224, s5, v208
	v_ashrrev_i32_e32 v225, 31, v224
	v_lshlrev_b64 v[224:225], 5, v[224:225]
	v_lshl_add_u64 v[224:225], v[76:77], 0, v[224:225]
	s_lshl_b32 s14, s10, 2
	s_mov_b32 s15, 0
	v_lshl_add_u64 v[224:225], v[224:225], 0, s[14:15]
	s_mov_b64 s[30:31], 0x7300000
	s_or_b32 s14, s10, s36
	v_lshl_add_u64 v[226:227], v[224:225], 0, s[30:31]
	s_lshl_b64 s[14:15], s[14:15], 2
	v_lshl_add_u64 v[228:229], v[2:3], 0, s[14:15]
	global_load_dword v232, v[226:227], off offset:16
	s_nop 0
	global_load_dword v233, v[228:229], off offset:16
	v_add_co_u32_e32 v224, vcc, 0x7300000, v224
	s_nop 1
	v_addc_co_u32_e32 v225, vcc, 0, v225, vcc
	global_load_dword v234, v[224:225], off
	s_nop 0
	global_load_dword v235, v[228:229], off
	s_mov_b64 exec, s[28:29]
	v_lshl_add_u64 v[6:7], v[20:21], 0, v[6:7]
	v_lshl_add_u64 v[4:5], v[20:21], 0, v[4:5]
	v_lshl_add_u64 v[6:7], v[6:7], 0, v[166:167]
	v_lshl_add_u64 v[4:5], v[4:5], 0, v[166:167]
	v_lshl_add_u64 v[6:7], v[6:7], 0, v[18:19]
	v_lshl_add_u64 v[4:5], v[4:5], 0, v[18:19]
	global_load_dword v201, v[6:7], off
	global_load_dword v199, v[6:7], off offset:512
	global_load_dword v197, v[6:7], off offset:1024
	global_load_dword v194, v[6:7], off offset:1536
	global_load_dword v192, v[6:7], off offset:2048
	global_load_dword v190, v[6:7], off offset:2560
	global_load_dword v188, v[6:7], off offset:3072
	global_load_dword v186, v[6:7], off offset:3584
	global_load_dword v200, v[4:5], off
	global_load_dword v198, v[4:5], off offset:512
	global_load_dword v196, v[4:5], off offset:1024
	global_load_dword v195, v[4:5], off offset:1536
	global_load_dword v193, v[4:5], off offset:2048
	global_load_dword v191, v[4:5], off offset:2560
	global_load_dword v189, v[4:5], off offset:3072
	global_load_dword v187, v[4:5], off offset:3584
	v_add_co_u32_e32 v6, vcc, s91, v6
	s_mov_b64 s[2:3], 0x800
	s_nop 0
	v_addc_co_u32_e32 v7, vcc, 0, v7, vcc
	v_add_co_u32_e32 v4, vcc, s91, v4
	v_add_u32_e32 v19, s6, v97
	s_nop 0
	v_addc_co_u32_e32 v5, vcc, 0, v5, vcc
	global_load_dword v184, v[6:7], off
	global_load_dword v182, v[6:7], off offset:512
	global_load_dword v180, v[6:7], off offset:1024
	global_load_dword v178, v[6:7], off offset:1536
	global_load_dword v176, v[6:7], off offset:2048
	global_load_dword v165, v[6:7], off offset:2560
	global_load_dword v163, v[6:7], off offset:3072
	global_load_dword v162, v[6:7], off offset:3584
	global_load_dword v185, v[4:5], off
	global_load_dword v183, v[4:5], off offset:512
	global_load_dword v181, v[4:5], off offset:1024
	global_load_dword v179, v[4:5], off offset:1536
	global_load_dword v177, v[4:5], off offset:2048
	global_load_dword v169, v[4:5], off offset:2560
	global_load_dword v164, v[4:5], off offset:3072
	global_load_dword v161, v[4:5], off offset:3584
	v_and_b32_e32 v4, 0xffffff80, v51
	v_ashrrev_i32_e32 v5, 31, v4
	v_lshlrev_b32_e32 v6, 4, v64
	v_add_u32_e32 v8, 0x1000, v4
	v_and_b32_e32 v10, 0xf0, v6
	v_lshlrev_b64 v[6:7], 1, v[4:5]
	v_ashrrev_i32_e32 v9, 31, v8
	v_or_b32_e32 v6, v6, v10
	v_lshlrev_b64 v[8:9], 1, v[8:9]
	v_lshl_add_u64 v[6:7], v[76:77], 0, v[6:7]
	v_or_b32_e32 v8, v8, v10
	v_lshl_add_u64 v[6:7], v[6:7], 0, s[12:13]
	v_lshl_add_u64 v[8:9], v[76:77], 0, v[8:9]
	v_lshl_add_u64 v[8:9], v[8:9], 0, s[12:13]
	global_load_dwordx4 v[36:39], v[6:7], off
	global_load_dwordx4 v[32:35], v[8:9], off
	v_add_u32_e32 v6, 0x2000, v4
	v_add_u32_e32 v4, 0x3000, v4
	v_ashrrev_i32_e32 v7, 31, v6
	v_ashrrev_i32_e32 v5, 31, v4
	v_lshlrev_b64 v[6:7], 1, v[6:7]
	v_lshlrev_b64 v[4:5], 1, v[4:5]
	v_or_b32_e32 v6, v6, v10
	v_or_b32_e32 v4, v4, v10
	v_lshl_add_u64 v[6:7], v[76:77], 0, v[6:7]
	v_lshl_add_u64 v[4:5], v[76:77], 0, v[4:5]
	v_lshl_add_u64 v[6:7], v[6:7], 0, s[12:13]
	v_lshl_add_u64 v[4:5], v[4:5], 0, s[12:13]
	global_load_dwordx4 v[44:47], v[6:7], off
	global_load_dwordx4 v[40:43], v[4:5], off
	v_lshlrev_b32_e32 v4, 2, v204
	v_mov_b32_e32 v5, v167
	s_waitcnt vmcnt(40)
	v_lshl_add_u64 v[0:1], v[0:1], 0, v[4:5]
	v_lshl_add_u64 v[4:5], v[0:1], 0, s[2:3]
	v_lshl_add_u64 v[8:9], v[0:1], 0, s[8:9]
	v_lshl_add_u64 v[14:15], v[4:5], 0, s[8:9]
	s_lshl_b64 s[8:9], s[20:21], 2
	v_lshl_add_u64 v[16:17], v[0:1], 0, s[8:9]
	v_lshl_add_u64 v[22:23], v[4:5], 0, s[8:9]
	s_lshl_b64 s[8:9], s[22:23], 2
	v_lshl_add_u64 v[6:7], s[16:17], 2, v[0:1]
	v_lshl_add_u64 v[4:5], v[4:5], 0, s[8:9]
	v_lshl_add_u64 v[24:25], v[0:1], 0, s[8:9]
	global_load_dwordx2 v[10:11], v[6:7], off
	global_load_dwordx2 v[12:13], v[8:9], off
	global_load_dwordx2 v[0:1], v[14:15], off
	s_nop 0
	global_load_dwordx2 v[6:7], v[6:7], off offset:2048
	s_nop 0
	global_load_dwordx2 v[16:17], v[16:17], off
	s_nop 0
	global_load_dwordx2 v[14:15], v[24:25], off
	s_nop 0
	global_load_dwordx2 v[4:5], v[4:5], off
	s_nop 0
	global_load_dwordx2 v[8:9], v[22:23], off
	v_cmp_gt_i32_e64 s[8:9], 3, v19
	s_and_saveexec_b64 s[6:7], s[8:9]
	s_xor_b64 s[6:7], exec, s[6:7]
	v_mov_b64_e32 v[30:31], s[96:97]
	s_or_saveexec_b64 s[6:7], s[6:7]
	v_add_u32_e32 v22, s11, v19
	v_ashrrev_i32_e32 v23, 31, v22
	v_lshl_add_u64 v[28:29], v[22:23], 0, -3
	v_lshl_add_u64 v[26:27], v[22:23], 0, -2
	v_lshl_add_u64 v[24:25], v[22:23], 0, -1
	v_mov_b32_e32 v102, 0
	v_alignbit_b32 v55, v29, v28, 8
	v_lshlrev_b32_e32 v54, 9, v28
	v_alignbit_b32 v53, v27, v26, 8
	v_lshlrev_b32_e32 v28, 9, v26
	v_alignbit_b32 v26, v25, v24, 8
	v_lshlrev_b32_e32 v19, 9, v24
	v_mov_b32_e32 v104, 0
	v_mov_b32_e32 v105, 0
	s_xor_b64 exec, exec, s[6:7]
	s_cbranch_execz .LBB0_1311
	v_mad_u64_u32 v[48:49], s[14:15], v55, 49, s[96:97]
	v_mad_u32_u24 v49, v29, 49, v49
	v_lshlrev_b64 v[48:49], 17, v[48:49]
	v_lshl_add_u64 v[48:49], v[20:21], 0, v[48:49]
	v_and_b32_e32 v56, 0x1fe00, v54
	v_mov_b32_e32 v57, v167
	v_lshl_add_u64 v[48:49], v[48:49], 0, v[56:57]
	v_lshl_add_u64 v[48:49], v[48:49], 0, v[166:167]
	global_load_dword v102, v[48:49], off
	v_mad_u64_u32 v[48:49], s[14:15], v53, 49, s[96:97]
	v_mad_u32_u24 v49, v27, 49, v49
	v_lshlrev_b64 v[48:49], 17, v[48:49]
	v_lshl_add_u64 v[48:49], v[20:21], 0, v[48:49]
	v_and_b32_e32 v56, 0x1fe00, v28
	v_lshl_add_u64 v[48:49], v[48:49], 0, v[56:57]
	v_lshl_add_u64 v[48:49], v[48:49], 0, v[166:167]
	global_load_dword v104, v[48:49], off
	v_mad_u64_u32 v[48:49], s[14:15], v26, 49, s[96:97]
	v_mad_u32_u24 v49, v25, 49, v49
	v_lshlrev_b64 v[48:49], 17, v[48:49]
	v_lshl_add_u64 v[48:49], v[20:21], 0, v[48:49]
	v_and_b32_e32 v56, 0x1fe00, v19
	v_lshl_add_u64 v[48:49], v[48:49], 0, v[56:57]
	v_lshl_add_u64 v[48:49], v[48:49], 0, v[166:167]
	global_load_dword v105, v[48:49], off

.LBB0_1315:
	s_or_b64 exec, exec, s[6:7]
	v_mad_u64_u32 v[26:27], s[6:7], v56, 49, 0
	v_mad_u32_u24 v27, v23, 49, v27
	v_lshl_add_u64 v[22:23], v[48:49], 0, v[26:27]
	v_lshlrev_b64 v[22:23], 17, v[22:23]
	v_lshl_add_u64 v[22:23], v[20:21], 0, v[22:23]
	v_mov_b32_e32 v31, v167
	v_lshl_add_u64 v[22:23], v[22:23], 0, v[30:31]
	v_lshl_add_u64 v[22:23], v[22:23], 0, v[166:167]
	v_mad_u64_u32 v[24:25], s[6:7], v52, 49, 0
	global_load_dword v88, v[22:23], off
	global_load_dword v70, v[22:23], off offset:512
	global_load_dword v68, v[22:23], off offset:1024
	global_load_dword v67, v[22:23], off offset:1536
	global_load_dword v66, v[22:23], off offset:2048
	global_load_dword v65, v[22:23], off offset:2560
	global_load_dword v63, v[22:23], off offset:3072
	global_load_dword v62, v[22:23], off offset:3584
	v_add_co_u32_e32 v22, vcc, s91, v22
	v_mad_u32_u24 v25, v75, 49, v25
	s_nop 0
	v_addc_co_u32_e32 v23, vcc, 0, v23, vcc
	s_or_b32 s96, s96, 4
	global_load_dword v61, v[22:23], off
	global_load_dword v60, v[22:23], off offset:512
	global_load_dword v59, v[22:23], off offset:1024
	global_load_dword v58, v[22:23], off offset:1536
	global_load_dword v57, v[22:23], off offset:2048
	global_load_dword v56, v[22:23], off offset:2560
	global_load_dword v55, v[22:23], off offset:3072
	global_load_dword v54, v[22:23], off offset:3584
	v_lshl_add_u64 v[22:23], v[24:25], 0, s[96:97]
	v_lshlrev_b64 v[22:23], 17, v[22:23]
	v_lshl_add_u64 v[20:21], v[20:21], 0, v[22:23]
	v_mov_b32_e32 v19, v167
	v_lshl_add_u64 v[18:19], v[20:21], 0, v[18:19]
	v_lshl_add_u64 v[18:19], v[18:19], 0, v[166:167]
	global_load_dword v24, v[18:19], off
	global_load_dword v20, v[18:19], off offset:512
	global_load_dword v21, v[18:19], off offset:1024
	global_load_dword v22, v[18:19], off offset:1536
	global_load_dword v25, v[18:19], off offset:2048
	global_load_dword v23, v[18:19], off offset:2560
	global_load_dword v26, v[18:19], off offset:3072
	global_load_dword v27, v[18:19], off offset:3584
	v_add_co_u32_e32 v18, vcc, s91, v18
	s_nop 1
	v_addc_co_u32_e32 v19, vcc, 0, v19, vcc
	global_load_dword v29, v[18:19], off
	global_load_dword v28, v[18:19], off offset:512
	global_load_dword v30, v[18:19], off offset:1024
	global_load_dword v31, v[18:19], off offset:1536
	global_load_dword v49, v[18:19], off offset:2048
	global_load_dword v48, v[18:19], off offset:2560
	global_load_dword v52, v[18:19], off offset:3072
	global_load_dword v53, v[18:19], off offset:3584
	v_mov_b32_e32 v19, v208
	s_nop 0
	v_cmp_gt_i32_e64 s[8:9], s83, v19
	v_lshl_add_u32 v18, v19, 2, 0
	s_and_saveexec_b64 s[6:7], s[8:9]
	s_cbranch_execz .LBB0_1319
	s_mov_b32 s0, 0xbfb8aa3b
	v_and_b32_e32 v111, 64, v214
	v_add_u32_e32 v113, -1, v214
	v_cmp_lt_i32_e32 vcc, v113, v111
	v_and_b32_e32 v112, 63, v19
	v_cmp_eq_u32_e64 s[10:11], 63, v19
	s_waitcnt vmcnt(63)
	v_add_f32_e32 v2, v232, v233
	v_mul_f32_e64 v3, |v2|, s0
	v_exp_f32_e32 v107, v3
	v_cndmask_b32_e32 v3, v113, v214, vcc
	v_lshlrev_b32_e32 v110, 2, v3
	v_min_f32_e32 v113, 0, v2
	v_add_f32_e32 v114, 1.0, v107
	v_add_f32_e32 v115, -1.0, v114
	v_frexp_mant_f32_e32 v116, v114
	v_cvt_f64_f32_e32 v[2:3], v114
	s_mov_b32 s0, 0x3f2aaaab
	v_sub_f32_e32 v117, v115, v114
	v_frexp_exp_i32_f64_e32 v2, v[2:3]
	v_cmp_gt_f32_e32 vcc, s0, v116
	v_sub_f32_e32 v115, v107, v115
	v_add_f32_e32 v3, 1.0, v117
	v_subbrev_co_u32_e32 v2, vcc, 0, v2, vcc
	v_add_f32_e32 v3, v115, v3
	v_sub_u32_e32 v115, 0, v2
	v_cvt_f32_i32_e32 v2, v2
	v_ldexp_f32 v114, v114, v115
	v_ldexp_f32 v3, v3, v115
	v_add_f32_e32 v115, -1.0, v114
	v_add_f32_e32 v116, 1.0, v114
	v_add_f32_e32 v117, 1.0, v115
	v_add_f32_e32 v118, -1.0, v116
	v_sub_f32_e32 v117, v114, v117
	v_sub_f32_e32 v114, v114, v118
	v_mul_f32_e32 v118, 0x3f317218, v2
	v_add_f32_e32 v117, v3, v117
	v_add_f32_e32 v3, v3, v114
	v_fma_f32 v114, v2, s56, -v118
	v_add_f32_e32 v119, v115, v117
	v_add_f32_e32 v120, v116, v3
	v_fmac_f32_e32 v114, 0xb102e308, v2
	v_sub_f32_e32 v2, v119, v115
	v_sub_f32_e32 v115, v120, v116
	v_rcp_f32_e32 v116, v120
	v_add_f32_e32 v121, v118, v114
	v_sub_f32_e32 v3, v3, v115
	v_sub_f32_e32 v115, v121, v118
	v_sub_f32_e32 v114, v114, v115
	v_mul_f32_e32 v115, v119, v116
	v_sub_f32_e32 v2, v117, v2
	v_mul_f32_e32 v117, v120, v115
	v_fma_f32 v118, v115, v120, -v117
	v_fmac_f32_e32 v118, v115, v3
	v_add_f32_e32 v122, v117, v118
	v_sub_f32_e32 v123, v119, v122
	v_sub_f32_e32 v117, v122, v117
	v_sub_f32_e32 v119, v119, v123
	v_sub_f32_e32 v117, v117, v118
	v_sub_f32_e32 v118, v119, v122
	v_add_f32_e32 v2, v2, v118
	v_add_f32_e32 v2, v117, v2
	v_add_f32_e32 v117, v123, v2
	v_mul_f32_e32 v118, v116, v117
	v_sub_f32_e32 v119, v123, v117
	v_mul_f32_e32 v122, v120, v118
	v_add_f32_e32 v2, v2, v119
	v_add_f32_e32 v119, v115, v118
	v_fma_f32 v120, v118, v120, -v122
	v_sub_f32_e32 v115, v119, v115
	v_fmac_f32_e32 v120, v118, v3
	v_sub_f32_e32 v3, v118, v115
	v_add_f32_e32 v115, v122, v120
	v_sub_f32_e32 v118, v115, v122
	v_sub_f32_e32 v122, v117, v115
	v_sub_f32_e32 v117, v117, v122
	v_sub_f32_e32 v115, v117, v115
	v_sub_f32_e32 v118, v118, v120
	v_add_f32_e32 v2, v2, v115
	v_add_f32_e32 v2, v118, v2
	v_add_f32_e32 v2, v122, v2
	v_mul_f32_e32 v2, v116, v2
	v_add_f32_e32 v2, v3, v2
	v_add_f32_e32 v3, v119, v2
	v_mul_f32_e32 v115, v3, v3
	v_fmamk_f32 v118, v115, 0x3e9b6dac, v217
	v_sub_f32_e32 v116, v3, v119
	v_ldexp_f32 v117, v3, 1
	v_mul_f32_e32 v3, v3, v115
	v_fmaak_f32 v115, v115, v118, 0x3f2aaada
	v_mul_f32_e32 v3, v3, v115
	v_add_f32_e32 v115, v117, v3
	v_sub_f32_e32 v2, v2, v116
	v_sub_f32_e32 v116, v115, v117
	v_ldexp_f32 v2, v2, 1
	v_sub_f32_e32 v3, v3, v116
	v_add_f32_e32 v2, v2, v3
	v_add_f32_e32 v3, v115, v2
	v_sub_f32_e32 v115, v3, v115
	v_add_f32_e32 v116, v121, v3
	v_sub_f32_e32 v2, v2, v115
	v_sub_f32_e32 v115, v116, v121
	v_sub_f32_e32 v117, v116, v115
	v_sub_f32_e32 v3, v3, v115
	v_add_f32_e32 v115, v114, v2
	v_sub_f32_e32 v117, v121, v117
	v_sub_f32_e32 v118, v115, v114
	v_add_f32_e32 v3, v3, v117
	v_sub_f32_e32 v117, v115, v118
	v_sub_f32_e32 v2, v2, v118
	v_sub_f32_e32 v114, v114, v117
	v_add_f32_e32 v3, v115, v3
	v_add_f32_e32 v2, v2, v114
	v_add_f32_e32 v114, v116, v3
	v_sub_f32_e32 v115, v114, v116
	v_sub_f32_e32 v3, v3, v115
	v_add_f32_e32 v2, v2, v3
	v_add_f32_e32 v2, v114, v2
	v_cmp_neq_f32_e32 vcc, s55, v107
	s_nop 1
	v_cndmask_b32_e32 v2, v209, v2, vcc
	v_cmp_ngt_f32_e32 vcc, -1.0, v107
	s_nop 1
	v_cndmask_b32_e32 v2, v252, v2, vcc
	v_cmp_neq_f32_e32 vcc, -1.0, v107
	s_nop 1
	v_cndmask_b32_e32 v2, v215, v2, vcc
	v_cmp_lt_f32_e64 vcc, |v107|, s57
	s_nop 1
	v_cndmask_b32_e32 v2, v2, v107, vcc
	v_sub_f32_e32 v2, v113, v2
	ds_bpermute_b32 v3, v110, v2
	v_add_u32_e32 v107, -2, v214
	v_cmp_lt_i32_e32 vcc, v107, v111
	s_waitcnt lgkmcnt(0)
	v_add_f32_e32 v3, v2, v3
	v_cndmask_b32_e32 v107, v107, v214, vcc
	v_cmp_eq_u32_e32 vcc, 0, v112
	v_lshlrev_b32_e32 v107, 2, v107
	s_nop 0
	v_cndmask_b32_e32 v2, v3, v2, vcc
	ds_bpermute_b32 v3, v107, v2
	v_add_u32_e32 v107, -4, v214
	v_cmp_lt_i32_e32 vcc, v107, v111
	s_waitcnt lgkmcnt(0)
	v_add_f32_e32 v3, v2, v3
	v_cndmask_b32_e32 v107, v107, v214, vcc
	v_cmp_gt_u32_e32 vcc, 2, v112
	v_lshlrev_b32_e32 v107, 2, v107
	s_nop 0
	v_cndmask_b32_e32 v2, v3, v2, vcc
	ds_bpermute_b32 v3, v107, v2
	v_add_u32_e32 v107, -8, v214
	v_cmp_lt_i32_e32 vcc, v107, v111
	s_waitcnt lgkmcnt(0)
	v_add_f32_e32 v3, v2, v3
	v_cndmask_b32_e32 v107, v107, v214, vcc
	v_cmp_gt_u32_e32 vcc, 4, v112
	v_lshlrev_b32_e32 v107, 2, v107
	s_nop 0
	v_cndmask_b32_e32 v2, v3, v2, vcc
	ds_bpermute_b32 v3, v107, v2
	v_add_u32_e32 v107, -16, v214
	v_cmp_lt_i32_e32 vcc, v107, v111
	s_waitcnt lgkmcnt(0)
	v_add_f32_e32 v3, v2, v3
	v_cndmask_b32_e32 v107, v107, v214, vcc
	v_cmp_gt_u32_e32 vcc, 8, v112
	v_lshlrev_b32_e32 v107, 2, v107
	s_nop 0
	v_cndmask_b32_e32 v2, v3, v2, vcc
	ds_bpermute_b32 v3, v107, v2
	v_subrev_u32_e32 v107, 32, v214
	v_cmp_lt_i32_e32 vcc, v107, v111
	s_waitcnt lgkmcnt(0)
	v_add_f32_e32 v3, v2, v3
	v_cndmask_b32_e32 v107, v107, v214, vcc
	v_cmp_gt_u32_e32 vcc, 16, v112
	v_lshlrev_b32_e32 v107, 2, v107
	s_nop 0
	v_cndmask_b32_e32 v2, v3, v2, vcc
	ds_bpermute_b32 v3, v107, v2
	v_cmp_gt_u32_e32 vcc, 32, v112
	s_waitcnt vmcnt(63)
	v_add_f32_e32 v107, v234, v235
	ds_write_b32 v18, v107 offset:512
	s_waitcnt lgkmcnt(1)
	v_add_f32_e32 v3, v2, v3
	s_and_saveexec_b64 s[14:15], s[10:11]
	ds_write_b32 v167, v3 offset:1024
	s_or_b64 exec, exec, s[14:15]
	v_cndmask_b32_e32 v107, v3, v2, vcc
